# grid barrier: non-leader workgroups poll the top generation word directly (one release hop less), leader no longer bumps the per-XCD generation word
# speedup vs baseline: 1.0068x; 1.0068x over previous
; __device__ __forceinline__ unsigned xb_ld(unsigned* p)              { return __hip_atomic_load(p, __ATOMIC_RELAXED, __HIP_MEMORY_SCOPE_AGENT); }
; __device__ __forceinline__ unsigned xb_add(unsigned* p, unsigned v) { return __hip_atomic_fetch_add(p, v, __ATOMIC_RELAXED, __HIP_MEMORY_SCOPE_AGENT); }
; #define XB_SPIN(cond, bar) do { unsigned _sp = 0; while (cond) { \
;     if ((++_sp & 255u) == 0u) { if (xb_ld(&(bar)[XB_TMO])) break; if (_sp > XB_SPIN_CAP) { atomicAdd(&(bar)[XB_TMO], 1u); break; } } } } while (0)
; __device__ __forceinline__ void xcd_barrier(unsigned* barw, volatile LAS unsigned* stw, const int wv) {
;     ...
;         const unsigned old = xb_add(&bar[XB_XSUB(b.x)], 1u);
;         const unsigned gen = old / nloc;
;         if (old + 1u == (gen + 1u) * nloc) {
;             __builtin_amdgcn_fence(__ATOMIC_RELEASE, "agent");
;             asm volatile("s_waitcnt vmcnt(0)" ::: "memory");
;             const unsigned og = xb_add(&bar[XB_TOP], 1u);
;             const unsigned tg = og / nx;
;             if (og + 1u == (tg + 1u) * nx) xb_add(&bar[XB_TOPGEN], 1u);
;             else XB_SPIN(xb_ld(&bar[XB_TOPGEN]) == tg, bar);
;             __builtin_amdgcn_fence(__ATOMIC_ACQUIRE, "agent");
;             xb_add(&bar[XB_XGEN(b.x)], 1u);
;             asm volatile("s_waitcnt vmcnt(0)" ::: "memory");
;         } else {
;             XB_SPIN(xb_ld(&bar[XB_XGEN(b.x)]) == gen, bar);
.LBB0_113:
	s_or_b64 exec, exec, s[18:19]
	v_cvt_f32_u32_e32 v4, v2
	s_waitcnt vmcnt(0)
	v_readfirstlane_b32 s3, v3
	v_sub_u32_e32 v3, 0, v2
	v_rcp_iflag_f32_e32 v4, v4
	v_add_u32_e32 v5, s3, v1
	v_mul_f32_e32 v4, 0x4f7ffffe, v4
	v_cvt_u32_f32_e32 v4, v4
	v_mul_lo_u32 v1, v3, v4
	v_mul_hi_u32 v1, v4, v1
	v_add_u32_e32 v1, v4, v1
	v_mul_hi_u32 v1, v5, v1
	v_mul_lo_u32 v3, v1, v2
	v_sub_u32_e32 v3, v5, v3
	v_add_u32_e32 v4, 1, v1
	v_cmp_ge_u32_e32 vcc, v3, v2
	s_nop 1
	v_cndmask_b32_e32 v1, v1, v4, vcc
	v_sub_u32_e32 v4, v3, v2
	v_cndmask_b32_e32 v3, v3, v4, vcc
	v_add_u32_e32 v4, 1, v1
	v_cmp_ge_u32_e32 vcc, v3, v2
	v_add_u32_e32 v3, 1, v5
	s_nop 0
	v_cndmask_b32_e32 v1, v1, v4, vcc
	v_mul_lo_u32 v4, v2, v1
	v_add_u32_e32 v2, v4, v2
	v_cmp_ne_u32_e32 vcc, v3, v2
	s_and_saveexec_b64 s[4:5], vcc
	s_xor_b64 s[16:17], exec, s[4:5]
	s_cbranch_execz .LBB0_127
	s_waitcnt lgkmcnt(0)
	v_mov_b32_e32 v0, 0x3100
	global_load_dword v0, v0, s[12:13] offset:1024 sc1
	s_add_u32 s20, s12, 0x3500
	s_addc_u32 s21, s13, 0
	s_waitcnt vmcnt(0)
	v_cmp_eq_u32_e32 vcc, v0, v1
	s_and_saveexec_b64 s[18:19], vcc
	s_cbranch_execz .LBB0_126
	s_mov_b32 s3, 1
	s_mov_b64 s[22:23], 0
	v_mov_b32_e32 v0, 0
	s_branch .LBB0_117

; __device__ __forceinline__ unsigned xb_add(unsigned* p, unsigned v) { return __hip_atomic_fetch_add(p, v, __ATOMIC_RELAXED, __HIP_MEMORY_SCOPE_AGENT); }
; __device__ __forceinline__ void xcd_barrier(unsigned* barw, volatile LAS unsigned* stw, const int wv) {
;     ...
;             __builtin_amdgcn_fence(__ATOMIC_ACQUIRE, "agent");
;             xb_add(&bar[XB_XGEN(b.x)], 1u);
;             asm volatile("s_waitcnt vmcnt(0)" ::: "memory");
.LBB0_144:
	s_or_b64 exec, exec, s[10:11]
	s_mov_b64 s[10:11], exec
	v_mbcnt_lo_u32_b32 v0, s10, 0
	v_mbcnt_hi_u32_b32 v0, s11, v0
	v_cmp_eq_u32_e32 vcc, 0, v0
	s_waitcnt vmcnt(0)
	buffer_inv sc1
	s_and_saveexec_b64 s[12:13], vcc
	s_cbranch_execz .LBB0_146
.LBB0_146:
	s_or_b64 exec, exec, s[12:13]
	s_waitcnt vmcnt(0)

; __device__ __forceinline__ unsigned xb_ld(unsigned* p)              { return __hip_atomic_load(p, __ATOMIC_RELAXED, __HIP_MEMORY_SCOPE_AGENT); }
; __device__ __forceinline__ unsigned xb_add(unsigned* p, unsigned v) { return __hip_atomic_fetch_add(p, v, __ATOMIC_RELAXED, __HIP_MEMORY_SCOPE_AGENT); }
; #define XB_SPIN(cond, bar) do { unsigned _sp = 0; while (cond) { \
;     if ((++_sp & 255u) == 0u) { if (xb_ld(&(bar)[XB_TMO])) break; if (_sp > XB_SPIN_CAP) { atomicAdd(&(bar)[XB_TMO], 1u); break; } } } } while (0)
; __device__ __forceinline__ void xcd_barrier(unsigned* barw, volatile LAS unsigned* stw, const int wv) {
;     ...
;         const unsigned old = xb_add(&bar[XB_XSUB(b.x)], 1u);
;         const unsigned gen = old / nloc;
;         if (old + 1u == (gen + 1u) * nloc) {
;             __builtin_amdgcn_fence(__ATOMIC_RELEASE, "agent");
;             asm volatile("s_waitcnt vmcnt(0)" ::: "memory");
;             const unsigned og = xb_add(&bar[XB_TOP], 1u);
;             const unsigned tg = og / nx;
;             if (og + 1u == (tg + 1u) * nx) xb_add(&bar[XB_TOPGEN], 1u);
;             else XB_SPIN(xb_ld(&bar[XB_TOPGEN]) == tg, bar);
;             __builtin_amdgcn_fence(__ATOMIC_ACQUIRE, "agent");
;             xb_add(&bar[XB_XGEN(b.x)], 1u);
;             asm volatile("s_waitcnt vmcnt(0)" ::: "memory");
;         } else {
;             XB_SPIN(xb_ld(&bar[XB_XGEN(b.x)]) == gen, bar);
.LBB0_181:
	s_or_b64 exec, exec, s[18:19]
	v_cvt_f32_u32_e32 v4, v2
	s_waitcnt vmcnt(0)
	v_readfirstlane_b32 s4, v3
	v_sub_u32_e32 v3, 0, v2
	v_rcp_iflag_f32_e32 v4, v4
	v_add_u32_e32 v5, s4, v1
	v_mul_f32_e32 v4, 0x4f7ffffe, v4
	v_cvt_u32_f32_e32 v4, v4
	v_mul_lo_u32 v1, v3, v4
	v_mul_hi_u32 v1, v4, v1
	v_add_u32_e32 v1, v4, v1
	v_mul_hi_u32 v1, v5, v1
	v_mul_lo_u32 v3, v1, v2
	v_sub_u32_e32 v3, v5, v3
	v_add_u32_e32 v4, 1, v1
	v_cmp_ge_u32_e32 vcc, v3, v2
	s_nop 1
	v_cndmask_b32_e32 v1, v1, v4, vcc
	v_sub_u32_e32 v4, v3, v2
	v_cndmask_b32_e32 v3, v3, v4, vcc
	v_add_u32_e32 v4, 1, v1
	v_cmp_ge_u32_e32 vcc, v3, v2
	v_add_u32_e32 v3, 1, v5
	s_nop 0
	v_cndmask_b32_e32 v1, v1, v4, vcc
	v_mul_lo_u32 v4, v2, v1
	v_add_u32_e32 v2, v4, v2
	v_cmp_ne_u32_e32 vcc, v3, v2
	s_and_saveexec_b64 s[4:5], vcc
	s_xor_b64 s[16:17], exec, s[4:5]
	s_cbranch_execz .LBB0_195
	s_waitcnt lgkmcnt(0)
	v_mov_b32_e32 v0, 0x3100
	global_load_dword v0, v0, s[10:11] offset:1024 sc1
	s_add_u32 s20, s10, 0x3500
	s_addc_u32 s21, s11, 0
	s_waitcnt vmcnt(0)
	v_cmp_eq_u32_e32 vcc, v0, v1
	s_and_saveexec_b64 s[18:19], vcc
	s_cbranch_execz .LBB0_194
	s_mov_b32 s4, 1
	s_mov_b64 s[22:23], 0
	v_mov_b32_e32 v0, 0
	s_branch .LBB0_185

; __device__ __forceinline__ unsigned xb_add(unsigned* p, unsigned v) { return __hip_atomic_fetch_add(p, v, __ATOMIC_RELAXED, __HIP_MEMORY_SCOPE_AGENT); }
; __device__ __forceinline__ void xcd_barrier(unsigned* barw, volatile LAS unsigned* stw, const int wv) {
;     ...
;             __builtin_amdgcn_fence(__ATOMIC_ACQUIRE, "agent");
;             xb_add(&bar[XB_XGEN(b.x)], 1u);
;             asm volatile("s_waitcnt vmcnt(0)" ::: "memory");
.LBB0_212:
	s_or_b64 exec, exec, s[10:11]
	s_mov_b64 s[10:11], exec
	v_mbcnt_lo_u32_b32 v0, s10, 0
	v_mbcnt_hi_u32_b32 v0, s11, v0
	v_cmp_eq_u32_e32 vcc, 0, v0
	s_waitcnt vmcnt(0)
	buffer_inv sc1
	s_and_saveexec_b64 s[12:13], vcc
	s_cbranch_execz .LBB0_214
.LBB0_214:
	s_or_b64 exec, exec, s[12:13]
	s_waitcnt vmcnt(0)

; __device__ __forceinline__ unsigned xb_add(unsigned* p, unsigned v) { return __hip_atomic_fetch_add(p, v, __ATOMIC_RELAXED, __HIP_MEMORY_SCOPE_AGENT); }
; __device__ __forceinline__ void xcd_barrier(unsigned* barw, volatile LAS unsigned* stw, const int wv) {
;     ...
;             __builtin_amdgcn_fence(__ATOMIC_ACQUIRE, "agent");
;             xb_add(&bar[XB_XGEN(b.x)], 1u);
;             asm volatile("s_waitcnt vmcnt(0)" ::: "memory");
.LBB0_282:
	s_or_b64 exec, exec, s[10:11]
	s_mov_b64 s[10:11], exec
	v_mbcnt_lo_u32_b32 v0, s10, 0
	v_mbcnt_hi_u32_b32 v0, s11, v0
	v_cmp_eq_u32_e32 vcc, 0, v0
	s_waitcnt vmcnt(0)
	buffer_inv sc1
	s_and_saveexec_b64 s[12:13], vcc
	s_cbranch_execz .LBB0_284
.LBB0_284:
	s_or_b64 exec, exec, s[12:13]
	s_waitcnt vmcnt(0)

; __device__ __forceinline__ unsigned xb_ld(unsigned* p)              { return __hip_atomic_load(p, __ATOMIC_RELAXED, __HIP_MEMORY_SCOPE_AGENT); }
; __device__ __forceinline__ unsigned xb_add(unsigned* p, unsigned v) { return __hip_atomic_fetch_add(p, v, __ATOMIC_RELAXED, __HIP_MEMORY_SCOPE_AGENT); }
; #define XB_SPIN(cond, bar) do { unsigned _sp = 0; while (cond) { \
;     if ((++_sp & 255u) == 0u) { if (xb_ld(&(bar)[XB_TMO])) break; if (_sp > XB_SPIN_CAP) { atomicAdd(&(bar)[XB_TMO], 1u); break; } } } } while (0)
; __device__ __forceinline__ void xcd_barrier(unsigned* barw, volatile LAS unsigned* stw, const int wv) {
;     ...
;         const unsigned old = xb_add(&bar[XB_XSUB(b.x)], 1u);
;         const unsigned gen = old / nloc;
;         if (old + 1u == (gen + 1u) * nloc) {
;             __builtin_amdgcn_fence(__ATOMIC_RELEASE, "agent");
;             asm volatile("s_waitcnt vmcnt(0)" ::: "memory");
;             const unsigned og = xb_add(&bar[XB_TOP], 1u);
;             const unsigned tg = og / nx;
;             if (og + 1u == (tg + 1u) * nx) xb_add(&bar[XB_TOPGEN], 1u);
;             else XB_SPIN(xb_ld(&bar[XB_TOPGEN]) == tg, bar);
;             __builtin_amdgcn_fence(__ATOMIC_ACQUIRE, "agent");
;             xb_add(&bar[XB_XGEN(b.x)], 1u);
;             asm volatile("s_waitcnt vmcnt(0)" ::: "memory");
;         } else {
;             XB_SPIN(xb_ld(&bar[XB_XGEN(b.x)]) == gen, bar);
.LBB0_325:
	s_or_b64 exec, exec, s[18:19]
	v_cvt_f32_u32_e32 v4, v2
	s_waitcnt vmcnt(0)
	v_readfirstlane_b32 s4, v3
	v_sub_u32_e32 v3, 0, v2
	v_rcp_iflag_f32_e32 v4, v4
	v_add_u32_e32 v5, s4, v1
	v_mul_f32_e32 v4, 0x4f7ffffe, v4
	v_cvt_u32_f32_e32 v4, v4
	v_mul_lo_u32 v1, v3, v4
	v_mul_hi_u32 v1, v4, v1
	v_add_u32_e32 v1, v4, v1
	v_mul_hi_u32 v1, v5, v1
	v_mul_lo_u32 v3, v1, v2
	v_sub_u32_e32 v3, v5, v3
	v_add_u32_e32 v4, 1, v1
	v_cmp_ge_u32_e32 vcc, v3, v2
	s_nop 1
	v_cndmask_b32_e32 v1, v1, v4, vcc
	v_sub_u32_e32 v4, v3, v2
	v_cndmask_b32_e32 v3, v3, v4, vcc
	v_add_u32_e32 v4, 1, v1
	v_cmp_ge_u32_e32 vcc, v3, v2
	v_add_u32_e32 v3, 1, v5
	s_nop 0
	v_cndmask_b32_e32 v1, v1, v4, vcc
	v_mul_lo_u32 v4, v2, v1
	v_add_u32_e32 v2, v4, v2
	v_cmp_ne_u32_e32 vcc, v3, v2
	s_and_saveexec_b64 s[4:5], vcc
	s_xor_b64 s[16:17], exec, s[4:5]
	s_cbranch_execz .LBB0_339
	s_waitcnt lgkmcnt(0)
	v_mov_b32_e32 v0, 0x3100
	global_load_dword v0, v0, s[14:15] offset:1024 sc1
	s_add_u32 s20, s14, 0x3500
	s_addc_u32 s21, s15, 0
	s_waitcnt vmcnt(0)
	v_cmp_eq_u32_e32 vcc, v0, v1
	s_and_saveexec_b64 s[18:19], vcc
	s_cbranch_execz .LBB0_338
	s_mov_b32 s4, 1
	s_mov_b64 s[22:23], 0
	v_mov_b32_e32 v0, 0
	s_branch .LBB0_329

; __device__ __forceinline__ unsigned xb_add(unsigned* p, unsigned v) { return __hip_atomic_fetch_add(p, v, __ATOMIC_RELAXED, __HIP_MEMORY_SCOPE_AGENT); }
; __device__ __forceinline__ void xcd_barrier(unsigned* barw, volatile LAS unsigned* stw, const int wv) {
;     ...
;             __builtin_amdgcn_fence(__ATOMIC_ACQUIRE, "agent");
;             xb_add(&bar[XB_XGEN(b.x)], 1u);
;             asm volatile("s_waitcnt vmcnt(0)" ::: "memory");
.LBB0_356:
	s_or_b64 exec, exec, s[10:11]
	s_mov_b64 s[10:11], exec
	v_mbcnt_lo_u32_b32 v0, s10, 0
	v_mbcnt_hi_u32_b32 v0, s11, v0
	v_cmp_eq_u32_e32 vcc, 0, v0
	s_waitcnt vmcnt(0)
	buffer_inv sc1
	s_and_saveexec_b64 s[14:15], vcc
	s_cbranch_execz .LBB0_358
.LBB0_358:
	s_or_b64 exec, exec, s[14:15]
	s_waitcnt vmcnt(0)

; __device__ __forceinline__ unsigned xb_add(unsigned* p, unsigned v) { return __hip_atomic_fetch_add(p, v, __ATOMIC_RELAXED, __HIP_MEMORY_SCOPE_AGENT); }
; __device__ __forceinline__ void xcd_barrier(unsigned* barw, volatile LAS unsigned* stw, const int wv) {
;     ...
;             __builtin_amdgcn_fence(__ATOMIC_ACQUIRE, "agent");
;             xb_add(&bar[XB_XGEN(b.x)], 1u);
;             asm volatile("s_waitcnt vmcnt(0)" ::: "memory");
.LBB0_428:
	s_or_b64 exec, exec, s[10:11]
	s_mov_b64 s[10:11], exec
	v_mbcnt_lo_u32_b32 v0, s10, 0
	v_mbcnt_hi_u32_b32 v0, s11, v0
	v_cmp_eq_u32_e32 vcc, 0, v0
	s_waitcnt vmcnt(0)
	buffer_inv sc1
	s_and_saveexec_b64 s[12:13], vcc
	s_cbranch_execz .LBB0_430
.LBB0_430:
	s_or_b64 exec, exec, s[12:13]
	s_waitcnt vmcnt(0)

; __device__ __forceinline__ unsigned xb_ld(unsigned* p)              { return __hip_atomic_load(p, __ATOMIC_RELAXED, __HIP_MEMORY_SCOPE_AGENT); }
; __device__ __forceinline__ unsigned xb_add(unsigned* p, unsigned v) { return __hip_atomic_fetch_add(p, v, __ATOMIC_RELAXED, __HIP_MEMORY_SCOPE_AGENT); }
; #define XB_SPIN(cond, bar) do { unsigned _sp = 0; while (cond) { \
;     if ((++_sp & 255u) == 0u) { if (xb_ld(&(bar)[XB_TMO])) break; if (_sp > XB_SPIN_CAP) { atomicAdd(&(bar)[XB_TMO], 1u); break; } } } } while (0)
; __device__ __forceinline__ void xcd_barrier(unsigned* barw, volatile LAS unsigned* stw, const int wv) {
;     ...
;         const unsigned old = xb_add(&bar[XB_XSUB(b.x)], 1u);
;         const unsigned gen = old / nloc;
;         if (old + 1u == (gen + 1u) * nloc) {
;             __builtin_amdgcn_fence(__ATOMIC_RELEASE, "agent");
;             asm volatile("s_waitcnt vmcnt(0)" ::: "memory");
;             const unsigned og = xb_add(&bar[XB_TOP], 1u);
;             const unsigned tg = og / nx;
;             if (og + 1u == (tg + 1u) * nx) xb_add(&bar[XB_TOPGEN], 1u);
;             else XB_SPIN(xb_ld(&bar[XB_TOPGEN]) == tg, bar);
;             __builtin_amdgcn_fence(__ATOMIC_ACQUIRE, "agent");
;             xb_add(&bar[XB_XGEN(b.x)], 1u);
;             asm volatile("s_waitcnt vmcnt(0)" ::: "memory");
;         } else {
;             XB_SPIN(xb_ld(&bar[XB_XGEN(b.x)]) == gen, bar);
.LBB0_481:
	s_or_b64 exec, exec, s[18:19]
	v_cvt_f32_u32_e32 v4, v2
	s_waitcnt vmcnt(0)
	v_readfirstlane_b32 s4, v3
	v_sub_u32_e32 v3, 0, v2
	v_rcp_iflag_f32_e32 v4, v4
	v_add_u32_e32 v5, s4, v1
	v_mul_f32_e32 v4, 0x4f7ffffe, v4
	v_cvt_u32_f32_e32 v4, v4
	v_mul_lo_u32 v1, v3, v4
	v_mul_hi_u32 v1, v4, v1
	v_add_u32_e32 v1, v4, v1
	v_mul_hi_u32 v1, v5, v1
	v_mul_lo_u32 v3, v1, v2
	v_sub_u32_e32 v3, v5, v3
	v_add_u32_e32 v4, 1, v1
	v_cmp_ge_u32_e32 vcc, v3, v2
	s_nop 1
	v_cndmask_b32_e32 v1, v1, v4, vcc
	v_sub_u32_e32 v4, v3, v2
	v_cndmask_b32_e32 v3, v3, v4, vcc
	v_add_u32_e32 v4, 1, v1
	v_cmp_ge_u32_e32 vcc, v3, v2
	v_add_u32_e32 v3, 1, v5
	s_nop 0
	v_cndmask_b32_e32 v1, v1, v4, vcc
	v_mul_lo_u32 v4, v2, v1
	v_add_u32_e32 v2, v4, v2
	v_cmp_ne_u32_e32 vcc, v3, v2
	s_and_saveexec_b64 s[4:5], vcc
	s_xor_b64 s[14:15], exec, s[4:5]
	s_cbranch_execz .LBB0_495
	s_waitcnt lgkmcnt(0)
	v_mov_b32_e32 v0, 0x3100
	global_load_dword v0, v0, s[16:17] offset:1024 sc1
	s_add_u32 s20, s16, 0x3500
	s_addc_u32 s21, s17, 0
	s_waitcnt vmcnt(0)
	v_cmp_eq_u32_e32 vcc, v0, v1
	s_and_saveexec_b64 s[18:19], vcc
	s_cbranch_execz .LBB0_494
	s_mov_b32 s4, 1
	s_mov_b64 s[22:23], 0
	v_mov_b32_e32 v0, 0
	s_branch .LBB0_485

; __device__ __forceinline__ unsigned xb_add(unsigned* p, unsigned v) { return __hip_atomic_fetch_add(p, v, __ATOMIC_RELAXED, __HIP_MEMORY_SCOPE_AGENT); }
; __device__ __forceinline__ void xcd_barrier(unsigned* barw, volatile LAS unsigned* stw, const int wv) {
;     ...
;             __builtin_amdgcn_fence(__ATOMIC_ACQUIRE, "agent");
;             xb_add(&bar[XB_XGEN(b.x)], 1u);
;             asm volatile("s_waitcnt vmcnt(0)" ::: "memory");
.LBB0_512:
	s_or_b64 exec, exec, s[10:11]
	s_mov_b64 s[10:11], exec
	v_mbcnt_lo_u32_b32 v0, s10, 0
	v_mbcnt_hi_u32_b32 v0, s11, v0
	v_cmp_eq_u32_e32 vcc, 0, v0
	s_waitcnt vmcnt(0)
	buffer_inv sc1
	s_and_saveexec_b64 s[14:15], vcc
	s_cbranch_execz .LBB0_514
.LBB0_514:
	s_or_b64 exec, exec, s[14:15]
	s_waitcnt vmcnt(0)

; __device__ __forceinline__ unsigned xb_add(unsigned* p, unsigned v) { return __hip_atomic_fetch_add(p, v, __ATOMIC_RELAXED, __HIP_MEMORY_SCOPE_AGENT); }
; __device__ __forceinline__ void xcd_barrier(unsigned* barw, volatile LAS unsigned* stw, const int wv) {
;     ...
;             __builtin_amdgcn_fence(__ATOMIC_ACQUIRE, "agent");
;             xb_add(&bar[XB_XGEN(b.x)], 1u);
;             asm volatile("s_waitcnt vmcnt(0)" ::: "memory");
.LBB0_586:
	s_or_b64 exec, exec, s[10:11]
	s_mov_b64 s[10:11], exec
	v_mbcnt_lo_u32_b32 v0, s10, 0
	v_mbcnt_hi_u32_b32 v0, s11, v0
	v_cmp_eq_u32_e32 vcc, 0, v0
	s_waitcnt vmcnt(0)
	buffer_inv sc1
	s_and_saveexec_b64 s[12:13], vcc
	s_cbranch_execz .LBB0_588
.LBB0_588:
	s_or_b64 exec, exec, s[12:13]
	s_waitcnt vmcnt(0)

; __device__ __forceinline__ unsigned xb_ld(unsigned* p)              { return __hip_atomic_load(p, __ATOMIC_RELAXED, __HIP_MEMORY_SCOPE_AGENT); }
; __device__ __forceinline__ unsigned xb_add(unsigned* p, unsigned v) { return __hip_atomic_fetch_add(p, v, __ATOMIC_RELAXED, __HIP_MEMORY_SCOPE_AGENT); }
; #define XB_SPIN(cond, bar) do { unsigned _sp = 0; while (cond) { \
;     if ((++_sp & 255u) == 0u) { if (xb_ld(&(bar)[XB_TMO])) break; if (_sp > XB_SPIN_CAP) { atomicAdd(&(bar)[XB_TMO], 1u); break; } } } } while (0)
; __device__ __forceinline__ void xcd_barrier(unsigned* barw, volatile LAS unsigned* stw, const int wv) {
;     ...
;         const unsigned old = xb_add(&bar[XB_XSUB(b.x)], 1u);
;         const unsigned gen = old / nloc;
;         if (old + 1u == (gen + 1u) * nloc) {
;             __builtin_amdgcn_fence(__ATOMIC_RELEASE, "agent");
;             asm volatile("s_waitcnt vmcnt(0)" ::: "memory");
;             const unsigned og = xb_add(&bar[XB_TOP], 1u);
;             const unsigned tg = og / nx;
;             if (og + 1u == (tg + 1u) * nx) xb_add(&bar[XB_TOPGEN], 1u);
;             else XB_SPIN(xb_ld(&bar[XB_TOPGEN]) == tg, bar);
;             __builtin_amdgcn_fence(__ATOMIC_ACQUIRE, "agent");
;             xb_add(&bar[XB_XGEN(b.x)], 1u);
;             asm volatile("s_waitcnt vmcnt(0)" ::: "memory");
;         } else {
;             XB_SPIN(xb_ld(&bar[XB_XGEN(b.x)]) == gen, bar);
.LBB0_740:
	s_lshl_b32 s4, s4, 8
	s_add_u32 s12, s10, s4
	s_addc_u32 s13, s11, 0
	v_mov_b32_e32 v1, 0x1000
	v_mov_b32_e32 v3, 1
	global_atomic_add v3, v1, v3, s[12:13] offset:1024 sc0
	v_cvt_f32_u32_e32 v1, v2
	v_sub_u32_e32 v4, 0, v2
	v_rcp_iflag_f32_e32 v1, v1
	s_nop 0
	v_mul_f32_e32 v1, 0x4f7ffffe, v1
	v_cvt_u32_f32_e32 v1, v1
	v_mul_lo_u32 v4, v4, v1
	v_mul_hi_u32 v4, v1, v4
	v_add_u32_e32 v1, v1, v4
	s_waitcnt vmcnt(0)
	v_mul_hi_u32 v1, v3, v1
	v_mul_lo_u32 v4, v1, v2
	v_sub_u32_e32 v4, v3, v4
	v_add_u32_e32 v5, 1, v1
	v_cmp_ge_u32_e32 vcc, v4, v2
	v_add_u32_e32 v3, 1, v3
	s_nop 0
	v_cndmask_b32_e32 v1, v1, v5, vcc
	v_sub_u32_e32 v5, v4, v2
	v_cndmask_b32_e32 v4, v4, v5, vcc
	v_add_u32_e32 v5, 1, v1
	v_cmp_ge_u32_e32 vcc, v4, v2
	s_nop 1
	v_cndmask_b32_e32 v1, v1, v5, vcc
	v_mul_lo_u32 v4, v2, v1
	v_add_u32_e32 v2, v4, v2
	v_cmp_ne_u32_e32 vcc, v3, v2
	s_and_saveexec_b64 s[4:5], vcc
	s_xor_b64 s[14:15], exec, s[4:5]
	s_cbranch_execz .LBB0_753
	s_waitcnt lgkmcnt(0)
	v_mov_b32_e32 v0, 0x3100
	global_load_dword v0, v0, s[10:11] offset:1024 sc1
	s_add_u32 s18, s10, 0x3500
	s_addc_u32 s19, s11, 0
	s_waitcnt vmcnt(0)
	v_cmp_eq_u32_e32 vcc, v0, v1
	s_and_saveexec_b64 s[16:17], vcc
	s_cbranch_execz .LBB0_752
	s_mov_b32 s4, 1
	s_mov_b64 s[20:21], 0
	v_mov_b32_e32 v0, 0
	s_branch .LBB0_744

; __device__ __forceinline__ unsigned xb_add(unsigned* p, unsigned v) { return __hip_atomic_fetch_add(p, v, __ATOMIC_RELAXED, __HIP_MEMORY_SCOPE_AGENT); }
; __device__ __forceinline__ void xcd_barrier(unsigned* barw, volatile LAS unsigned* stw, const int wv) {
;     ...
;             __builtin_amdgcn_fence(__ATOMIC_ACQUIRE, "agent");
;             xb_add(&bar[XB_XGEN(b.x)], 1u);
;             asm volatile("s_waitcnt vmcnt(0)" ::: "memory");
.LBB0_768:
	s_or_b64 exec, exec, s[8:9]
	s_waitcnt vmcnt(0)
	buffer_inv sc1
	s_waitcnt vmcnt(0)

; __device__ __forceinline__ unsigned xb_ld(unsigned* p)              { return __hip_atomic_load(p, __ATOMIC_RELAXED, __HIP_MEMORY_SCOPE_AGENT); }
; __device__ __forceinline__ unsigned xb_add(unsigned* p, unsigned v) { return __hip_atomic_fetch_add(p, v, __ATOMIC_RELAXED, __HIP_MEMORY_SCOPE_AGENT); }
; #define XB_SPIN(cond, bar) do { unsigned _sp = 0; while (cond) { \
;     if ((++_sp & 255u) == 0u) { if (xb_ld(&(bar)[XB_TMO])) break; if (_sp > XB_SPIN_CAP) { atomicAdd(&(bar)[XB_TMO], 1u); break; } } } } while (0)
; __device__ __forceinline__ void xcd_barrier(unsigned* barw, volatile LAS unsigned* stw, const int wv) {
;     ...
;         const unsigned old = xb_add(&bar[XB_XSUB(b.x)], 1u);
;         const unsigned gen = old / nloc;
;         if (old + 1u == (gen + 1u) * nloc) {
;             __builtin_amdgcn_fence(__ATOMIC_RELEASE, "agent");
;             asm volatile("s_waitcnt vmcnt(0)" ::: "memory");
;             const unsigned og = xb_add(&bar[XB_TOP], 1u);
;             const unsigned tg = og / nx;
;             if (og + 1u == (tg + 1u) * nx) xb_add(&bar[XB_TOPGEN], 1u);
;             else XB_SPIN(xb_ld(&bar[XB_TOPGEN]) == tg, bar);
;             __builtin_amdgcn_fence(__ATOMIC_ACQUIRE, "agent");
;             xb_add(&bar[XB_XGEN(b.x)], 1u);
;             asm volatile("s_waitcnt vmcnt(0)" ::: "memory");
;         } else {
;             XB_SPIN(xb_ld(&bar[XB_XGEN(b.x)]) == gen, bar);
.LBB0_800:
	s_lshl_b32 s0, s4, 8
	s_mov_b32 s1, 0
	v_lshl_add_u64 v[4:5], v[2:3], 0, s[0:1]
	v_add_co_u32_e32 v10, vcc, 0x1000, v4
	v_mov_b32_e32 v7, 1
	s_nop 0
	v_addc_co_u32_e32 v11, vcc, 0, v5, vcc
	global_atomic_add v7, v[10:11], v7, off offset:1024 sc0
	v_cvt_f32_u32_e32 v9, v8
	v_sub_u32_e32 v10, 0, v8
	v_rcp_iflag_f32_e32 v9, v9
	s_nop 0
	v_mul_f32_e32 v9, 0x4f7ffffe, v9
	v_cvt_u32_f32_e32 v9, v9
	v_mul_lo_u32 v10, v10, v9
	v_mul_hi_u32 v10, v9, v10
	v_add_u32_e32 v9, v9, v10
	s_waitcnt vmcnt(0)
	v_mul_hi_u32 v9, v7, v9
	v_mul_lo_u32 v11, v9, v8
	v_add_u32_e32 v10, 1, v7
	v_sub_u32_e32 v7, v7, v11
	v_add_u32_e32 v12, 1, v9
	v_cmp_ge_u32_e32 vcc, v7, v8
	v_sub_u32_e32 v11, v7, v8
	s_nop 0
	v_cndmask_b32_e32 v9, v9, v12, vcc
	v_cndmask_b32_e32 v7, v7, v11, vcc
	v_add_u32_e32 v11, 1, v9
	v_cmp_ge_u32_e32 vcc, v7, v8
	s_nop 1
	v_cndmask_b32_e32 v7, v9, v11, vcc
	v_mad_u64_u32 v[8:9], s[0:1], v8, v7, v[8:9]
	v_cmp_ne_u32_e32 vcc, v10, v8
	s_and_saveexec_b64 s[0:1], vcc
	s_xor_b64 s[0:1], exec, s[0:1]
	s_cbranch_execz .LBB0_813
	v_add_co_u32_e32 v2, vcc, 0x3500, v2
	s_nop 1
	v_addc_co_u32_e32 v3, vcc, 0, v3, vcc
	global_load_dword v4, v[2:3], off sc1
	s_waitcnt vmcnt(0)
	v_cmp_eq_u32_e32 vcc, v4, v7
	s_and_saveexec_b64 s[8:9], vcc
	s_cbranch_execz .LBB0_812
	s_mov_b32 s4, 1
	s_mov_b64 s[10:11], 0
	s_branch .LBB0_804

; __device__ __forceinline__ unsigned xb_add(unsigned* p, unsigned v) { return __hip_atomic_fetch_add(p, v, __ATOMIC_RELAXED, __HIP_MEMORY_SCOPE_AGENT); }
; __device__ __forceinline__ void xcd_barrier(unsigned* barw, volatile LAS unsigned* stw, const int wv) {
;     ...
;             __builtin_amdgcn_fence(__ATOMIC_ACQUIRE, "agent");
;             xb_add(&bar[XB_XGEN(b.x)], 1u);
;             asm volatile("s_waitcnt vmcnt(0)" ::: "memory");
.LBB0_828:
	s_or_b64 exec, exec, s[0:1]
	s_waitcnt vmcnt(0)
	buffer_inv sc1
	s_waitcnt vmcnt(0)

; __device__ __forceinline__ unsigned xb_ld(unsigned* p)              { return __hip_atomic_load(p, __ATOMIC_RELAXED, __HIP_MEMORY_SCOPE_AGENT); }
; __device__ __forceinline__ unsigned xb_add(unsigned* p, unsigned v) { return __hip_atomic_fetch_add(p, v, __ATOMIC_RELAXED, __HIP_MEMORY_SCOPE_AGENT); }
; #define XB_SPIN(cond, bar) do { unsigned _sp = 0; while (cond) { \
;     if ((++_sp & 255u) == 0u) { if (xb_ld(&(bar)[XB_TMO])) break; if (_sp > XB_SPIN_CAP) { atomicAdd(&(bar)[XB_TMO], 1u); break; } } } } while (0)
; __device__ __forceinline__ void xcd_barrier(unsigned* barw, volatile LAS unsigned* stw, const int wv) {
;     ...
;         const unsigned old = xb_add(&bar[XB_XSUB(b.x)], 1u);
;         const unsigned gen = old / nloc;
;         if (old + 1u == (gen + 1u) * nloc) {
;             __builtin_amdgcn_fence(__ATOMIC_RELEASE, "agent");
;             asm volatile("s_waitcnt vmcnt(0)" ::: "memory");
;             const unsigned og = xb_add(&bar[XB_TOP], 1u);
;             const unsigned tg = og / nx;
;             if (og + 1u == (tg + 1u) * nx) xb_add(&bar[XB_TOPGEN], 1u);
;             else XB_SPIN(xb_ld(&bar[XB_TOPGEN]) == tg, bar);
;             __builtin_amdgcn_fence(__ATOMIC_ACQUIRE, "agent");
;             xb_add(&bar[XB_XGEN(b.x)], 1u);
;             asm volatile("s_waitcnt vmcnt(0)" ::: "memory");
;         } else {
;             XB_SPIN(xb_ld(&bar[XB_XGEN(b.x)]) == gen, bar);
.LBB0_865:
	s_or_b64 exec, exec, s[16:17]
	v_cvt_f32_u32_e32 v4, v2
	s_waitcnt vmcnt(0)
	v_readfirstlane_b32 s4, v3
	v_sub_u32_e32 v3, 0, v2
	v_rcp_iflag_f32_e32 v4, v4
	v_add_u32_e32 v5, s4, v1
	v_mul_f32_e32 v4, 0x4f7ffffe, v4
	v_cvt_u32_f32_e32 v4, v4
	v_mul_lo_u32 v1, v3, v4
	v_mul_hi_u32 v1, v4, v1
	v_add_u32_e32 v1, v4, v1
	v_mul_hi_u32 v1, v5, v1
	v_mul_lo_u32 v3, v1, v2
	v_sub_u32_e32 v3, v5, v3
	v_add_u32_e32 v4, 1, v1
	v_cmp_ge_u32_e32 vcc, v3, v2
	s_nop 1
	v_cndmask_b32_e32 v1, v1, v4, vcc
	v_sub_u32_e32 v4, v3, v2
	v_cndmask_b32_e32 v3, v3, v4, vcc
	v_add_u32_e32 v4, 1, v1
	v_cmp_ge_u32_e32 vcc, v3, v2
	v_add_u32_e32 v3, 1, v5
	s_nop 0
	v_cndmask_b32_e32 v1, v1, v4, vcc
	v_mul_lo_u32 v4, v2, v1
	v_add_u32_e32 v2, v4, v2
	v_cmp_ne_u32_e32 vcc, v3, v2
	s_and_saveexec_b64 s[4:5], vcc
	s_xor_b64 s[14:15], exec, s[4:5]
	s_cbranch_execz .LBB0_879
	s_waitcnt lgkmcnt(0)
	v_mov_b32_e32 v0, 0x3100
	global_load_dword v0, v0, s[12:13] offset:1024 sc1
	s_add_u32 s18, s12, 0x3500
	s_addc_u32 s19, s13, 0
	s_waitcnt vmcnt(0)
	v_cmp_eq_u32_e32 vcc, v0, v1
	s_and_saveexec_b64 s[16:17], vcc
	s_cbranch_execz .LBB0_878
	s_mov_b32 s4, 1
	s_mov_b64 s[20:21], 0
	v_mov_b32_e32 v0, 0
	s_branch .LBB0_869

; __device__ __forceinline__ unsigned xb_add(unsigned* p, unsigned v) { return __hip_atomic_fetch_add(p, v, __ATOMIC_RELAXED, __HIP_MEMORY_SCOPE_AGENT); }
; __device__ __forceinline__ void xcd_barrier(unsigned* barw, volatile LAS unsigned* stw, const int wv) {
;     ...
;             __builtin_amdgcn_fence(__ATOMIC_ACQUIRE, "agent");
;             xb_add(&bar[XB_XGEN(b.x)], 1u);
;             asm volatile("s_waitcnt vmcnt(0)" ::: "memory");
.LBB0_896:
	s_or_b64 exec, exec, s[8:9]
	s_mov_b64 s[8:9], exec
	v_mbcnt_lo_u32_b32 v0, s8, 0
	v_mbcnt_hi_u32_b32 v0, s9, v0
	v_cmp_eq_u32_e32 vcc, 0, v0
	s_waitcnt vmcnt(0)
	buffer_inv sc1
	s_and_saveexec_b64 s[12:13], vcc
	s_cbranch_execz .LBB0_898
.LBB0_898:
	s_or_b64 exec, exec, s[12:13]
	s_waitcnt vmcnt(0)

; __device__ __forceinline__ unsigned xb_ld(unsigned* p)              { return __hip_atomic_load(p, __ATOMIC_RELAXED, __HIP_MEMORY_SCOPE_AGENT); }
; __device__ __forceinline__ unsigned xb_add(unsigned* p, unsigned v) { return __hip_atomic_fetch_add(p, v, __ATOMIC_RELAXED, __HIP_MEMORY_SCOPE_AGENT); }
; #define XB_SPIN(cond, bar) do { unsigned _sp = 0; while (cond) { \
;     if ((++_sp & 255u) == 0u) { if (xb_ld(&(bar)[XB_TMO])) break; if (_sp > XB_SPIN_CAP) { atomicAdd(&(bar)[XB_TMO], 1u); break; } } } } while (0)
; __device__ __forceinline__ void xcd_barrier(unsigned* barw, volatile LAS unsigned* stw, const int wv) {
;     ...
;         const unsigned old = xb_add(&bar[XB_XSUB(b.x)], 1u);
;         const unsigned gen = old / nloc;
;         if (old + 1u == (gen + 1u) * nloc) {
;             __builtin_amdgcn_fence(__ATOMIC_RELEASE, "agent");
;             asm volatile("s_waitcnt vmcnt(0)" ::: "memory");
;             const unsigned og = xb_add(&bar[XB_TOP], 1u);
;             const unsigned tg = og / nx;
;             if (og + 1u == (tg + 1u) * nx) xb_add(&bar[XB_TOPGEN], 1u);
;             else XB_SPIN(xb_ld(&bar[XB_TOPGEN]) == tg, bar);
;             __builtin_amdgcn_fence(__ATOMIC_ACQUIRE, "agent");
;             xb_add(&bar[XB_XGEN(b.x)], 1u);
;             asm volatile("s_waitcnt vmcnt(0)" ::: "memory");
;         } else {
;             XB_SPIN(xb_ld(&bar[XB_XGEN(b.x)]) == gen, bar);
.LBB0_959:
	s_or_b64 exec, exec, s[10:11]
	v_cvt_f32_u32_e32 v4, v2
	s_waitcnt vmcnt(0)
	v_readfirstlane_b32 s8, v3
	v_sub_u32_e32 v3, 0, v2
	v_rcp_iflag_f32_e32 v4, v4
	v_add_u32_e32 v5, s8, v1
	v_mul_f32_e32 v4, 0x4f7ffffe, v4
	v_cvt_u32_f32_e32 v4, v4
	v_mul_lo_u32 v1, v3, v4
	v_mul_hi_u32 v1, v4, v1
	v_add_u32_e32 v1, v4, v1
	v_mul_hi_u32 v1, v5, v1
	v_mul_lo_u32 v3, v1, v2
	v_sub_u32_e32 v3, v5, v3
	v_add_u32_e32 v4, 1, v1
	v_cmp_ge_u32_e32 vcc, v3, v2
	s_nop 1
	v_cndmask_b32_e32 v1, v1, v4, vcc
	v_sub_u32_e32 v4, v3, v2
	v_cndmask_b32_e32 v3, v3, v4, vcc
	v_add_u32_e32 v4, 1, v1
	v_cmp_ge_u32_e32 vcc, v3, v2
	v_add_u32_e32 v3, 1, v5
	s_nop 0
	v_cndmask_b32_e32 v1, v1, v4, vcc
	v_mul_lo_u32 v4, v2, v1
	v_add_u32_e32 v2, v4, v2
	v_cmp_ne_u32_e32 vcc, v3, v2
	s_and_saveexec_b64 s[8:9], vcc
	s_xor_b64 s[8:9], exec, s[8:9]
	s_cbranch_execz .LBB0_973
	s_waitcnt lgkmcnt(0)
	v_mov_b32_e32 v0, 0x3100
	global_load_dword v0, v0, s[12:13] offset:1024 sc1
	s_add_u32 s14, s12, 0x3500
	s_addc_u32 s15, s13, 0
	s_waitcnt vmcnt(0)
	v_cmp_eq_u32_e32 vcc, v0, v1
	s_and_saveexec_b64 s[10:11], vcc
	s_cbranch_execz .LBB0_972
	s_mov_b32 s26, 1
	s_mov_b64 s[16:17], 0
	v_mov_b32_e32 v0, 0
	s_branch .LBB0_963

; __device__ __forceinline__ unsigned xb_add(unsigned* p, unsigned v) { return __hip_atomic_fetch_add(p, v, __ATOMIC_RELAXED, __HIP_MEMORY_SCOPE_AGENT); }
; __device__ __forceinline__ void xcd_barrier(unsigned* barw, volatile LAS unsigned* stw, const int wv) {
;     ...
;             __builtin_amdgcn_fence(__ATOMIC_ACQUIRE, "agent");
;             xb_add(&bar[XB_XGEN(b.x)], 1u);
;             asm volatile("s_waitcnt vmcnt(0)" ::: "memory");
.LBB0_990:
	s_or_b64 exec, exec, s[4:5]
	s_mov_b64 s[4:5], exec
	v_mbcnt_lo_u32_b32 v0, s4, 0
	v_mbcnt_hi_u32_b32 v0, s5, v0
	v_cmp_eq_u32_e32 vcc, 0, v0
	s_waitcnt vmcnt(0)
	buffer_inv sc1
	s_and_saveexec_b64 s[8:9], vcc
	s_cbranch_execz .LBB0_992
.LBB0_992:
	s_or_b64 exec, exec, s[8:9]
	s_waitcnt vmcnt(0)

; __device__ __forceinline__ unsigned xb_ld(unsigned* p)              { return __hip_atomic_load(p, __ATOMIC_RELAXED, __HIP_MEMORY_SCOPE_AGENT); }
; __device__ __forceinline__ unsigned xb_add(unsigned* p, unsigned v) { return __hip_atomic_fetch_add(p, v, __ATOMIC_RELAXED, __HIP_MEMORY_SCOPE_AGENT); }
; #define XB_SPIN(cond, bar) do { unsigned _sp = 0; while (cond) { \
;     if ((++_sp & 255u) == 0u) { if (xb_ld(&(bar)[XB_TMO])) break; if (_sp > XB_SPIN_CAP) { atomicAdd(&(bar)[XB_TMO], 1u); break; } } } } while (0)
; __device__ __forceinline__ void xcd_barrier(unsigned* barw, volatile LAS unsigned* stw, const int wv) {
;     ...
;         const unsigned old = xb_add(&bar[XB_XSUB(b.x)], 1u);
;         const unsigned gen = old / nloc;
;         if (old + 1u == (gen + 1u) * nloc) {
;             __builtin_amdgcn_fence(__ATOMIC_RELEASE, "agent");
;             asm volatile("s_waitcnt vmcnt(0)" ::: "memory");
;             const unsigned og = xb_add(&bar[XB_TOP], 1u);
;             const unsigned tg = og / nx;
;             if (og + 1u == (tg + 1u) * nx) xb_add(&bar[XB_TOPGEN], 1u);
;             else XB_SPIN(xb_ld(&bar[XB_TOPGEN]) == tg, bar);
;             __builtin_amdgcn_fence(__ATOMIC_ACQUIRE, "agent");
;             xb_add(&bar[XB_XGEN(b.x)], 1u);
;             asm volatile("s_waitcnt vmcnt(0)" ::: "memory");
;         } else {
;             XB_SPIN(xb_ld(&bar[XB_XGEN(b.x)]) == gen, bar);
.LBB0_1031:
	s_or_b64 exec, exec, s[10:11]
	v_cvt_f32_u32_e32 v4, v2
	s_waitcnt vmcnt(0)
	v_readfirstlane_b32 s6, v3
	v_sub_u32_e32 v3, 0, v2
	v_rcp_iflag_f32_e32 v4, v4
	v_add_u32_e32 v5, s6, v1
	v_mul_f32_e32 v4, 0x4f7ffffe, v4
	v_cvt_u32_f32_e32 v4, v4
	v_mul_lo_u32 v1, v3, v4
	v_mul_hi_u32 v1, v4, v1
	v_add_u32_e32 v1, v4, v1
	v_mul_hi_u32 v1, v5, v1
	v_mul_lo_u32 v3, v1, v2
	v_sub_u32_e32 v3, v5, v3
	v_add_u32_e32 v4, 1, v1
	v_cmp_ge_u32_e32 vcc, v3, v2
	s_nop 1
	v_cndmask_b32_e32 v1, v1, v4, vcc
	v_sub_u32_e32 v4, v3, v2
	v_cndmask_b32_e32 v3, v3, v4, vcc
	v_add_u32_e32 v4, 1, v1
	v_cmp_ge_u32_e32 vcc, v3, v2
	v_add_u32_e32 v3, 1, v5
	s_nop 0
	v_cndmask_b32_e32 v1, v1, v4, vcc
	v_mul_lo_u32 v4, v2, v1
	v_add_u32_e32 v2, v4, v2
	v_cmp_ne_u32_e32 vcc, v3, v2
	s_and_saveexec_b64 s[6:7], vcc
	s_xor_b64 s[6:7], exec, s[6:7]
	s_cbranch_execz .LBB0_1045
	s_waitcnt lgkmcnt(0)
	v_mov_b32_e32 v0, 0x3100
	global_load_dword v0, v0, s[8:9] offset:1024 sc1
	s_add_u32 s12, s8, 0x3500
	s_addc_u32 s13, s9, 0
	s_waitcnt vmcnt(0)
	v_cmp_eq_u32_e32 vcc, v0, v1
	s_and_saveexec_b64 s[10:11], vcc
	s_cbranch_execz .LBB0_1044
	s_mov_b32 s24, 1
	s_mov_b64 s[14:15], 0
	v_mov_b32_e32 v0, 0
	s_branch .LBB0_1035

; __device__ __forceinline__ unsigned xb_add(unsigned* p, unsigned v) { return __hip_atomic_fetch_add(p, v, __ATOMIC_RELAXED, __HIP_MEMORY_SCOPE_AGENT); }
; __device__ __forceinline__ void xcd_barrier(unsigned* barw, volatile LAS unsigned* stw, const int wv) {
;     ...
;             __builtin_amdgcn_fence(__ATOMIC_ACQUIRE, "agent");
;             xb_add(&bar[XB_XGEN(b.x)], 1u);
;             asm volatile("s_waitcnt vmcnt(0)" ::: "memory");
.LBB0_1062:
	s_or_b64 exec, exec, s[2:3]
	s_mov_b64 s[2:3], exec
	v_mbcnt_lo_u32_b32 v0, s2, 0
	v_mbcnt_hi_u32_b32 v0, s3, v0
	v_cmp_eq_u32_e32 vcc, 0, v0
	s_waitcnt vmcnt(0)
	buffer_inv sc1
	s_and_saveexec_b64 s[6:7], vcc
	s_cbranch_execz .LBB0_1064
.LBB0_1064:
	s_or_b64 exec, exec, s[6:7]
	s_waitcnt vmcnt(0)

; __device__ __forceinline__ unsigned xb_ld(unsigned* p)              { return __hip_atomic_load(p, __ATOMIC_RELAXED, __HIP_MEMORY_SCOPE_AGENT); }
; __device__ __forceinline__ unsigned xb_add(unsigned* p, unsigned v) { return __hip_atomic_fetch_add(p, v, __ATOMIC_RELAXED, __HIP_MEMORY_SCOPE_AGENT); }
; #define XB_SPIN(cond, bar) do { unsigned _sp = 0; while (cond) { \
;     if ((++_sp & 255u) == 0u) { if (xb_ld(&(bar)[XB_TMO])) break; if (_sp > XB_SPIN_CAP) { atomicAdd(&(bar)[XB_TMO], 1u); break; } } } } while (0)
; __device__ __forceinline__ void xcd_barrier(unsigned* barw, volatile LAS unsigned* stw, const int wv) {
;     ...
;         const unsigned old = xb_add(&bar[XB_XSUB(b.x)], 1u);
;         const unsigned gen = old / nloc;
;         if (old + 1u == (gen + 1u) * nloc) {
;             __builtin_amdgcn_fence(__ATOMIC_RELEASE, "agent");
;             asm volatile("s_waitcnt vmcnt(0)" ::: "memory");
;             const unsigned og = xb_add(&bar[XB_TOP], 1u);
;             const unsigned tg = og / nx;
;             if (og + 1u == (tg + 1u) * nx) xb_add(&bar[XB_TOPGEN], 1u);
;             else XB_SPIN(xb_ld(&bar[XB_TOPGEN]) == tg, bar);
;             __builtin_amdgcn_fence(__ATOMIC_ACQUIRE, "agent");
;             xb_add(&bar[XB_XGEN(b.x)], 1u);
;             asm volatile("s_waitcnt vmcnt(0)" ::: "memory");
;         } else {
;             XB_SPIN(xb_ld(&bar[XB_XGEN(b.x)]) == gen, bar);
.LBB0_1101:
	s_or_b64 exec, exec, s[10:11]
	v_cvt_f32_u32_e32 v4, v2
	s_waitcnt vmcnt(0)
	v_readfirstlane_b32 s8, v3
	v_sub_u32_e32 v3, 0, v2
	v_rcp_iflag_f32_e32 v4, v4
	v_add_u32_e32 v5, s8, v1
	v_mul_f32_e32 v4, 0x4f7ffffe, v4
	v_cvt_u32_f32_e32 v4, v4
	v_mul_lo_u32 v1, v3, v4
	v_mul_hi_u32 v1, v4, v1
	v_add_u32_e32 v1, v4, v1
	v_mul_hi_u32 v1, v5, v1
	v_mul_lo_u32 v3, v1, v2
	v_sub_u32_e32 v3, v5, v3
	v_add_u32_e32 v4, 1, v1
	v_cmp_ge_u32_e32 vcc, v3, v2
	s_nop 1
	v_cndmask_b32_e32 v1, v1, v4, vcc
	v_sub_u32_e32 v4, v3, v2
	v_cndmask_b32_e32 v3, v3, v4, vcc
	v_add_u32_e32 v4, 1, v1
	v_cmp_ge_u32_e32 vcc, v3, v2
	v_add_u32_e32 v3, 1, v5
	s_nop 0
	v_cndmask_b32_e32 v1, v1, v4, vcc
	v_mul_lo_u32 v4, v2, v1
	v_add_u32_e32 v2, v4, v2
	v_cmp_ne_u32_e32 vcc, v3, v2
	s_and_saveexec_b64 s[8:9], vcc
	s_xor_b64 s[8:9], exec, s[8:9]
	s_cbranch_execz .LBB0_1115
	s_waitcnt lgkmcnt(0)
	v_mov_b32_e32 v0, 0x3100
	global_load_dword v0, v0, s[2:3] offset:1024 sc1
	s_add_u32 s12, s2, 0x3500
	s_addc_u32 s13, s3, 0
	s_waitcnt vmcnt(0)
	v_cmp_eq_u32_e32 vcc, v0, v1
	s_and_saveexec_b64 s[10:11], vcc
	s_cbranch_execz .LBB0_1114
	s_mov_b32 s24, 1
	s_mov_b64 s[14:15], 0
	v_mov_b32_e32 v0, 0
	s_branch .LBB0_1105

; __device__ __forceinline__ unsigned xb_add(unsigned* p, unsigned v) { return __hip_atomic_fetch_add(p, v, __ATOMIC_RELAXED, __HIP_MEMORY_SCOPE_AGENT); }
; __device__ __forceinline__ void xcd_barrier(unsigned* barw, volatile LAS unsigned* stw, const int wv) {
;     ...
;             __builtin_amdgcn_fence(__ATOMIC_ACQUIRE, "agent");
;             xb_add(&bar[XB_XGEN(b.x)], 1u);
;             asm volatile("s_waitcnt vmcnt(0)" ::: "memory");
.LBB0_1132:
	s_or_b64 exec, exec, s[2:3]
	s_mov_b64 s[2:3], exec
	v_mbcnt_lo_u32_b32 v0, s2, 0
	v_mbcnt_hi_u32_b32 v0, s3, v0
	v_cmp_eq_u32_e32 vcc, 0, v0
	s_waitcnt vmcnt(0)
	buffer_inv sc1
	s_and_saveexec_b64 s[4:5], vcc
	s_cbranch_execz .LBB0_1134
.LBB0_1134:
	s_or_b64 exec, exec, s[4:5]
	s_waitcnt vmcnt(0)
